# early-publication-of-first-image-item
# baseline (speedup 1.0000x reference)
.LBB0_243:
	s_or_b64 exec, exec, s[34:35]
	s_waitcnt lgkmcnt(0)
	s_barrier
	v_lshl_add_u64 v[56:57], v[56:57], 0, s[24:25]
	v_lshl_add_u64 v[58:59], v[58:59], 0, s[26:27]
	v_lshl_add_u64 v[60:61], v[60:61], 0, s[28:29]
	s_add_i32 s3, s3, s36
	s_andn2_b64 vcc, exec, s[30:31]
	s_add_i32 s37, s37, s40
	s_cbranch_vccz .Lp2_exit
	s_sub_u32 s98, s45, s74
	s_cmp_lg_u32 s98, s2
	s_cbranch_scc1 .Lp2_notfirst
	s_waitcnt vmcnt(0)
	s_barrier
	s_cmp_gt_u32 s101, 63
	s_cbranch_scc1 .Lp2_nopub
	s_lshl_b32 s98, s98, 2
	s_add_u32 s98, s98, 0x8000
	v_mov_b32_e32 v238, s98
	v_mov_b32_e32 v239, 1
	global_store_dword v238, v239, s[70:71] sc1
	s_branch .Lp2_nopub
.Lp2_notfirst:
	s_sub_u32 s98, s98, s74
	s_cmp_lt_i32 s98, s2
	s_cbranch_scc1 .Lp2_nopub
	s_cmp_gt_u32 s101, 63
	s_cbranch_scc1 .Lp2_nopub
	s_lshl_b32 s98, s98, 2
	s_add_u32 s98, s98, 0x8000
	v_mov_b32_e32 v238, s98
	v_mov_b32_e32 v239, 1
	global_store_dword v238, v239, s[70:71] sc1
